# speedup vs baseline: 1.0198x; 1.0009x over previous
.LBB0_171:
	s_nop 1
	v_max_f32_e32 v1, v83, v83
	v_max_f32_e32 v206, v82, v82
	v_max_f32_e32 v1, v206, v1
	v_max3_f32 v1, v1, v84, v85
	v_max3_f32 v1, v1, v86, v87
	v_max3_f32 v1, v1, v88, v89
	v_max3_f32 v1, v1, v90, v91
	v_max3_f32 v1, v1, v92, v93
	v_max3_f32 v1, v1, v94, v95
	v_max3_f32 v1, v1, v96, v97
	v_max3_f32 v1, v1, v66, v67
	v_max3_f32 v1, v1, v68, v69
	v_max3_f32 v1, v1, v70, v71
	v_max3_f32 v1, v1, v72, v73
	v_max3_f32 v1, v1, v74, v75
	v_max3_f32 v1, v1, v76, v77
	v_max3_f32 v1, v1, v78, v79
	v_max3_f32 v1, v1, v80, v81
	v_mov_b32_e32 v206, v1
	s_nop 1
	v_permlane32_swap_b32_e32 v1, v206
	v_max_f32_e32 v206, v206, v206
	v_max_f32_e32 v1, v1, v1
	v_max_f32_e32 v1, v1, v206
	v_sub_f32_e32 v206, v1, v233
	v_mul_f32_e32 v206, 0x3e000000, v206
	v_cmp_ge_f32_e32 vcc, s85, v206
	s_nop 0
	s_cmp_eq_u64 vcc, exec
	s_cbranch_scc1 .Lattn_fast_0
	v_max_f32_e32 v206, v233, v233
	v_max_f32_e32 v234, v206, v1
	v_sub_f32_e32 v1, v233, v234
	v_mul_f32_e32 v1, 0x3e38aa3b, v1
	v_exp_f32_e32 v1, v1
	s_mov_b64 s[8:9], 0
	v_cmp_gt_f32_e32 vcc, 1.0, v1
	s_cbranch_vccz .LBB0_175
	s_and_saveexec_b64 s[10:11], s[4:5]
	ds_write_b32 v159, v1 offset:128
	s_or_b64 exec, exec, s[10:11]
	s_waitcnt lgkmcnt(0)
	ds_read_b128 v[212:215], v161 offset:224
	ds_read_b128 v[236:239], v161 offset:192
	ds_read_b128 v[240:243], v161 offset:160
	ds_read_b128 v[244:247], v161 offset:128
	s_waitcnt lgkmcnt(3)
	v_pk_mul_f32 v[64:65], v[64:65], v[214:215]
	s_waitcnt lgkmcnt(2)
	v_pk_mul_f32 v[60:61], v[60:61], v[238:239]
	s_waitcnt lgkmcnt(1)
	v_pk_mul_f32 v[56:57], v[56:57], v[242:243]
	s_waitcnt lgkmcnt(0)
	v_pk_mul_f32 v[52:53], v[52:53], v[246:247]
	v_pk_mul_f32 v[62:63], v[62:63], v[212:213]
	v_pk_mul_f32 v[58:59], v[58:59], v[236:237]
	v_pk_mul_f32 v[54:55], v[54:55], v[240:241]
	v_pk_mul_f32 v[50:51], v[50:51], v[244:245]
	v_pk_mul_f32 v[48:49], v[48:49], v[214:215]
	v_pk_mul_f32 v[44:45], v[44:45], v[238:239]
	v_pk_mul_f32 v[40:41], v[40:41], v[242:243]
	v_pk_mul_f32 v[36:37], v[36:37], v[246:247]
	v_pk_mul_f32 v[46:47], v[46:47], v[212:213]
	v_pk_mul_f32 v[42:43], v[42:43], v[236:237]
	v_pk_mul_f32 v[38:39], v[38:39], v[240:241]
	v_pk_mul_f32 v[34:35], v[34:35], v[244:245]
	v_pk_mul_f32 v[32:33], v[32:33], v[214:215]
	v_pk_mul_f32 v[28:29], v[28:29], v[238:239]
	v_pk_mul_f32 v[24:25], v[24:25], v[242:243]
	v_pk_mul_f32 v[20:21], v[20:21], v[246:247]
	v_pk_mul_f32 v[30:31], v[30:31], v[212:213]
	v_pk_mul_f32 v[26:27], v[26:27], v[236:237]
	v_pk_mul_f32 v[22:23], v[22:23], v[240:241]
	v_pk_mul_f32 v[18:19], v[18:19], v[244:245]
	v_pk_mul_f32 v[16:17], v[16:17], v[214:215]
	v_pk_mul_f32 v[12:13], v[12:13], v[238:239]
	v_pk_mul_f32 v[8:9], v[8:9], v[242:243]
	v_pk_mul_f32 v[4:5], v[4:5], v[246:247]
	v_pk_mul_f32 v[14:15], v[14:15], v[212:213]
	v_pk_mul_f32 v[10:11], v[10:11], v[236:237]
	v_pk_mul_f32 v[6:7], v[6:7], v[240:241]
	v_pk_mul_f32 v[2:3], v[2:3], v[244:245]
	s_branch .LBB0_175
.Lattn_fast_0:
	v_mov_b32_e32 v1, 1.0
	s_mov_b64 s[8:9], -1

.LBB0_181:
	s_nop 1
	v_max_f32_e32 v206, v83, v83
	v_max_f32_e32 v212, v82, v82
	v_max_f32_e32 v206, v212, v206
	v_max3_f32 v206, v206, v84, v85
	v_max3_f32 v206, v206, v86, v87
	v_max3_f32 v206, v206, v88, v89
	v_max3_f32 v206, v206, v90, v91
	v_max3_f32 v206, v206, v92, v93
	v_max3_f32 v206, v206, v94, v95
	v_max3_f32 v206, v206, v96, v97
	v_max3_f32 v206, v206, v66, v67
	v_max3_f32 v206, v206, v68, v69
	v_max3_f32 v206, v206, v70, v71
	v_max3_f32 v206, v206, v72, v73
	v_max3_f32 v206, v206, v74, v75
	v_max3_f32 v206, v206, v76, v77
	v_max3_f32 v206, v206, v78, v79
	v_max3_f32 v206, v206, v80, v81
	v_mov_b32_e32 v212, v206
	s_nop 1
	v_permlane32_swap_b32_e32 v206, v212
	v_max_f32_e32 v212, v212, v212
	v_max_f32_e32 v206, v206, v206
	v_max_f32_e32 v206, v206, v212
	v_sub_f32_e32 v212, v206, v233
	v_mul_f32_e32 v212, 0x3e000000, v212
	v_cmp_ge_f32_e32 vcc, s85, v212
	s_nop 0
	s_cmp_eq_u64 vcc, exec
	s_cbranch_scc1 .Lattn_fast_1
	v_max_f32_e32 v212, v233, v233
	v_max_f32_e32 v237, v212, v206
	v_sub_f32_e32 v206, v233, v237
	v_mul_f32_e32 v206, 0x3e38aa3b, v206
	v_exp_f32_e32 v206, v206
	s_mov_b64 s[8:9], 0
	v_mov_b32_e32 v236, v206
	v_cmp_gt_f32_e32 vcc, 1.0, v236
	s_cbranch_vccz .LBB0_185
	s_and_saveexec_b64 s[10:11], s[4:5]
	ds_write_b32 v159, v236 offset:128
	s_or_b64 exec, exec, s[10:11]
	s_waitcnt lgkmcnt(0)
	ds_read_b128 v[212:215], v161 offset:224
	ds_read_b128 v[238:241], v161 offset:192
	ds_read_b128 v[242:245], v161 offset:160
	ds_read_b128 v[246:249], v161 offset:128
	s_waitcnt lgkmcnt(3)
	v_pk_mul_f32 v[64:65], v[64:65], v[214:215]
	s_waitcnt lgkmcnt(2)
	v_pk_mul_f32 v[60:61], v[60:61], v[240:241]
	s_waitcnt lgkmcnt(1)
	v_pk_mul_f32 v[56:57], v[56:57], v[244:245]
	s_waitcnt lgkmcnt(0)
	v_pk_mul_f32 v[52:53], v[52:53], v[248:249]
	v_pk_mul_f32 v[62:63], v[62:63], v[212:213]
	v_pk_mul_f32 v[58:59], v[58:59], v[238:239]
	v_pk_mul_f32 v[54:55], v[54:55], v[242:243]
	v_pk_mul_f32 v[50:51], v[50:51], v[246:247]
	v_pk_mul_f32 v[48:49], v[48:49], v[214:215]
	v_pk_mul_f32 v[44:45], v[44:45], v[240:241]
	v_pk_mul_f32 v[40:41], v[40:41], v[244:245]
	v_pk_mul_f32 v[36:37], v[36:37], v[248:249]
	v_pk_mul_f32 v[46:47], v[46:47], v[212:213]
	v_pk_mul_f32 v[42:43], v[42:43], v[238:239]
	v_pk_mul_f32 v[38:39], v[38:39], v[242:243]
	v_pk_mul_f32 v[34:35], v[34:35], v[246:247]
	v_pk_mul_f32 v[32:33], v[32:33], v[214:215]
	v_pk_mul_f32 v[28:29], v[28:29], v[240:241]
	v_pk_mul_f32 v[24:25], v[24:25], v[244:245]
	v_pk_mul_f32 v[20:21], v[20:21], v[248:249]
	v_pk_mul_f32 v[30:31], v[30:31], v[212:213]
	v_pk_mul_f32 v[26:27], v[26:27], v[238:239]
	v_pk_mul_f32 v[22:23], v[22:23], v[242:243]
	v_pk_mul_f32 v[18:19], v[18:19], v[246:247]
	v_pk_mul_f32 v[16:17], v[16:17], v[214:215]
	v_pk_mul_f32 v[12:13], v[12:13], v[240:241]
	v_pk_mul_f32 v[8:9], v[8:9], v[244:245]
	v_pk_mul_f32 v[4:5], v[4:5], v[248:249]
	v_pk_mul_f32 v[14:15], v[14:15], v[212:213]
	v_pk_mul_f32 v[10:11], v[10:11], v[238:239]
	v_pk_mul_f32 v[6:7], v[6:7], v[242:243]
	v_pk_mul_f32 v[2:3], v[2:3], v[246:247]
	s_branch .LBB0_185
.Lattn_fast_1:
	v_mov_b32_e32 v236, 1.0
	s_mov_b64 s[8:9], -1
